# removed the per-segment s_setprio flips from the in-projection GEMM main loop (on top of sc1 epilogue stores)
# speedup vs baseline: 1.0103x; 1.0103x over previous
; #define PG8_STAGE(bufoff, gbase, voff) do { _Pragma("unroll") for (int _i = 0; _i < 2; ++_i) \
;         __builtin_amdgcn_global_load_lds((const unsigned*)((const char*)(gbase) + (voff)[_i]), (LAS unsigned*)(lds + (bufoff) + ldsw + _i * 8192), 16, 0, 0); } while (0)
; #define PG8_LDA(dst, b, h) do { _Pragma("unroll") for (int m = 0; m < 4; ++m) _Pragma("unroll") for (int k = 0; k < 2; ++k) dst[m][k] = *(const LAS bf16x8*)(lds + PG8_SA(b, h) + aoff + m * 2048 + k * 1024); } while (0)
; #define PG8_LDB(dst, b, h) do { _Pragma("unroll") for (int n = 0; n < 2; ++n) _Pragma("unroll") for (int k = 0; k < 2; ++k) dst[n][k] = *(const LAS bf16x8*)(lds + PG8_SB(b, h) + boff + n * 2048 + k * 1024); } while (0)
; #define PG8_MMA(ai, bj, At, Bt) do { __builtin_amdgcn_s_setprio(1); _Pragma("unroll") for (int m = 0; m < 4; ++m) _Pragma("unroll") for (int n = 0; n < 2; ++n) _Pragma("unroll") for (int k = 0; k < 2; ++k) \
;         acc[ai][bj][m][n] = __builtin_amdgcn_mfma_f32_16x16x32_bf16(Bt[n][k], At[m][k], acc[ai][bj][m][n], 0, 0, 0); __builtin_amdgcn_s_setprio(0); } while (0)
; #define PG8_WAIT_V(n) asm volatile("s_waitcnt vmcnt(" #n ")" ::: "memory")
; #define PG8_WAIT_L(n) asm volatile("s_waitcnt lgkmcnt(" #n ")" ::: "memory")
; #define PG8_BAR __builtin_amdgcn_s_barrier()
; #define PG8_SCHED __builtin_amdgcn_sched_barrier(0)
; template <class Epi, class Sched>
; __device__ __forceinline__ void gemm_phase(LAS unsigned char* lds, const Gemm g, const Sched& S, const Epi& E, const int tid) {
;     ...
;             PG8_LDB(B0, 0, 0); PG8_LDB(B1, 0, 1); PG8_SCHED; PG8_LDA(At, 0, 0); PG8_STAGE(PG8_SA(1, 1), a1 + hstepA, voffA);
;             PG8_WAIT_V(8); PG8_WAIT_L(0); PG8_BAR; PG8_MMA(0, 0, At, B0); PG8_MMA(0, 1, At, B1); PG8_BAR; PG8_SCHED;
;             PG8_LDA(At, 0, 1); PG8_STAGE(PG8_SB(0, 0), b2, voffB); PG8_STAGE(PG8_SB(0, 1), b2 + hstepB, voffB); PG8_STAGE(PG8_SA(0, 0), a2, voffA);
.LBB0_347:
	s_add_u32 s24, s2, 0xfff80080
	s_addc_u32 s26, s3, -1
	s_add_i32 s31, 0, 0x10000
	s_cmp_eq_u32 s22, 28
	s_cselect_b32 s49, s15, s26
	s_cselect_b32 s48, s16, s24
	s_cselect_b32 s39, s11, s21
	s_cselect_b32 s38, s19, s20
	s_add_i32 s24, 0, 0x14000
	v_add_u32_e32 v140, s31, v158
	v_add_u32_e32 v154, s24, v158
	ds_read_b128 v[128:131], v140
	ds_read_b128 v[132:135], v140 offset:1024
	ds_read_b128 v[136:139], v140 offset:2048
	ds_read_b128 v[140:143], v140 offset:3072
	ds_read_b128 v[160:163], v154
	ds_read_b128 v[164:167], v154 offset:1024
	ds_read_b128 v[168:171], v154 offset:2048
	ds_read_b128 v[172:175], v154 offset:3072
	v_lshl_add_u64 v[154:155], s[2:3], 0, v[150:151]
	s_add_i32 m0, s45, 0xc000
	ds_read_b128 v[176:179], v159
	ds_read_b128 v[180:183], v159 offset:1024
	ds_read_b128 v[184:187], v159 offset:2048
	ds_read_b128 v[188:191], v159 offset:3072
	ds_read_b128 v[202:205], v159 offset:4096
	ds_read_b128 v[206:209], v159 offset:5120
	ds_read_b128 v[210:213], v159 offset:6144
	ds_read_b128 v[214:217], v159 offset:7168
	global_load_lds_dwordx4 v[154:155], off
	v_lshl_add_u64 v[154:155], s[2:3], 0, v[152:153]
	s_add_i32 m0, s45, 0xe000
	s_nop 0
	global_load_lds_dwordx4 v[154:155], off
	s_waitcnt vmcnt(8)
	s_waitcnt lgkmcnt(0)
	s_barrier
	s_waitcnt lgkmcnt(0)
	v_mfma_f32_16x16x32_bf16 v[124:127], v[128:131], v[176:179], v[124:127]
	v_mfma_f32_16x16x32_bf16 v[120:123], v[136:139], v[176:179], v[120:123]
	v_mfma_f32_16x16x32_bf16 v[108:111], v[128:131], v[184:187], v[108:111]
	v_mfma_f32_16x16x32_bf16 v[104:107], v[136:139], v[184:187], v[104:107]
	v_mfma_f32_16x16x32_bf16 v[92:95], v[128:131], v[202:205], v[92:95]
	v_mfma_f32_16x16x32_bf16 v[88:91], v[136:139], v[202:205], v[88:91]
	v_mfma_f32_16x16x32_bf16 v[76:79], v[128:131], v[210:213], v[76:79]
	v_mfma_f32_16x16x32_bf16 v[72:75], v[136:139], v[210:213], v[72:75]
	v_mfma_f32_16x16x32_bf16 v[124:127], v[132:135], v[180:183], v[124:127]
	v_mfma_f32_16x16x32_bf16 v[120:123], v[140:143], v[180:183], v[120:123]
	v_mfma_f32_16x16x32_bf16 v[108:111], v[132:135], v[188:191], v[108:111]
	v_mfma_f32_16x16x32_bf16 v[104:107], v[140:143], v[188:191], v[104:107]
	v_mfma_f32_16x16x32_bf16 v[92:95], v[132:135], v[206:209], v[92:95]
	v_mfma_f32_16x16x32_bf16 v[88:91], v[140:143], v[206:209], v[88:91]
	v_mfma_f32_16x16x32_bf16 v[76:79], v[132:135], v[214:217], v[76:79]
	v_mfma_f32_16x16x32_bf16 v[72:75], v[140:143], v[214:217], v[72:75]
	v_mfma_f32_16x16x32_bf16 v[116:119], v[160:163], v[176:179], v[116:119]
	v_mfma_f32_16x16x32_bf16 v[112:115], v[168:171], v[176:179], v[112:115]
	v_mfma_f32_16x16x32_bf16 v[100:103], v[160:163], v[184:187], v[100:103]
	v_mfma_f32_16x16x32_bf16 v[96:99], v[168:171], v[184:187], v[96:99]
	v_mfma_f32_16x16x32_bf16 v[84:87], v[160:163], v[202:205], v[84:87]
	v_mfma_f32_16x16x32_bf16 v[80:83], v[168:171], v[202:205], v[80:83]
	v_mfma_f32_16x16x32_bf16 v[68:71], v[160:163], v[210:213], v[68:71]
	v_mfma_f32_16x16x32_bf16 v[64:67], v[168:171], v[210:213], v[64:67]
	v_mfma_f32_16x16x32_bf16 v[116:119], v[164:167], v[180:183], v[116:119]
	v_mfma_f32_16x16x32_bf16 v[112:115], v[172:175], v[180:183], v[112:115]
	v_mfma_f32_16x16x32_bf16 v[100:103], v[164:167], v[188:191], v[100:103]
	v_mfma_f32_16x16x32_bf16 v[96:99], v[172:175], v[188:191], v[96:99]
	v_mfma_f32_16x16x32_bf16 v[84:87], v[164:167], v[206:209], v[84:87]
	v_mfma_f32_16x16x32_bf16 v[80:83], v[172:175], v[206:209], v[80:83]
	v_mfma_f32_16x16x32_bf16 v[68:71], v[164:167], v[214:217], v[68:71]
	v_mfma_f32_16x16x32_bf16 v[64:67], v[172:175], v[214:217], v[64:67]
	s_barrier
	s_add_i32 s26, s31, s25
	v_lshl_add_u64 v[154:155], s[38:39], 0, v[192:193]
	s_mov_b32 m0, s26
	ds_read_b128 v[176:179], v159 offset:16384
	ds_read_b128 v[180:183], v159 offset:17408
	ds_read_b128 v[184:187], v159 offset:18432
	ds_read_b128 v[188:191], v159 offset:19456
	ds_read_b128 v[202:205], v159 offset:20480
	ds_read_b128 v[206:209], v159 offset:21504
	ds_read_b128 v[210:213], v159 offset:22528
	ds_read_b128 v[214:217], v159 offset:23552
	global_load_lds_dwordx4 v[154:155], off
	s_add_i32 m0, s26, 0x2000
	s_add_u32 s64, s38, 0x80000
	v_lshl_add_u64 v[218:219], s[38:39], 0, v[148:149]
	s_addc_u32 s65, s39, 0
	s_add_i32 s24, s24, s25
	global_load_lds_dwordx4 v[218:219], off
	v_lshl_add_u64 v[220:221], s[64:65], 0, v[192:193]
	s_mov_b32 m0, s24
	v_lshl_add_u64 v[222:223], s[48:49], 0, v[146:147]
	global_load_lds_dwordx4 v[220:221], off
	v_lshl_add_u64 v[220:221], s[64:65], 0, v[148:149]
	s_add_i32 m0, s24, 0x2000
	s_nop 0
	global_load_lds_dwordx4 v[220:221], off
	v_lshl_add_u64 v[220:221], s[48:49], 0, v[144:145]
	s_mov_b32 m0, s45
	s_nop 0
	global_load_lds_dwordx4 v[220:221], off
	s_mov_b32 m0, s47
	s_nop 0
	global_load_lds_dwordx4 v[222:223], off
	s_waitcnt vmcnt(8)
	s_waitcnt lgkmcnt(0)
	s_barrier
; #define PG8_STAGE(bufoff, gbase, voff) do { _Pragma("unroll") for (int _i = 0; _i < 2; ++_i) \
;         __builtin_amdgcn_global_load_lds((const unsigned*)((const char*)(gbase) + (voff)[_i]), (LAS unsigned*)(lds + (bufoff) + ldsw + _i * 8192), 16, 0, 0); } while (0)
; #define PG8_LDA(dst, b, h) do { _Pragma("unroll") for (int m = 0; m < 4; ++m) _Pragma("unroll") for (int k = 0; k < 2; ++k) dst[m][k] = *(const LAS bf16x8*)(lds + PG8_SA(b, h) + aoff + m * 2048 + k * 1024); } while (0)
; #define PG8_LDB(dst, b, h) do { _Pragma("unroll") for (int n = 0; n < 2; ++n) _Pragma("unroll") for (int k = 0; k < 2; ++k) dst[n][k] = *(const LAS bf16x8*)(lds + PG8_SB(b, h) + boff + n * 2048 + k * 1024); } while (0)
; #define PG8_MMA(ai, bj, At, Bt) do { __builtin_amdgcn_s_setprio(1); _Pragma("unroll") for (int m = 0; m < 4; ++m) _Pragma("unroll") for (int n = 0; n < 2; ++n) _Pragma("unroll") for (int k = 0; k < 2; ++k) \
;         acc[ai][bj][m][n] = __builtin_amdgcn_mfma_f32_16x16x32_bf16(Bt[n][k], At[m][k], acc[ai][bj][m][n], 0, 0, 0); __builtin_amdgcn_s_setprio(0); } while (0)
; #define PG8_WAIT_V(n) asm volatile("s_waitcnt vmcnt(" #n ")" ::: "memory")
; #define PG8_WAIT_L(n) asm volatile("s_waitcnt lgkmcnt(" #n ")" ::: "memory")
; #define PG8_BAR __builtin_amdgcn_s_barrier()
; #define PG8_SCHED __builtin_amdgcn_sched_barrier(0)
; template <class Epi, class Sched>
; __device__ __forceinline__ void gemm_phase(LAS unsigned char* lds, const Gemm g, const Sched& S, const Epi& E, const int tid) {
;     ...
;             PG8_WAIT_V(8); PG8_WAIT_L(0); PG8_BAR; PG8_MMA(1, 0, At, B0); PG8_MMA(1, 1, At, B1); PG8_BAR; PG8_SCHED;
;             PG8_LDB(B0, 1, 0); PG8_LDB(B1, 1, 1); PG8_SCHED; PG8_LDA(At, 1, 0); PG8_STAGE(PG8_SA(0, 1), a2 + hstepA, voffA);
;             PG8_WAIT_V(8); PG8_WAIT_L(0); PG8_BAR; PG8_MMA(0, 0, At, B0); PG8_MMA(0, 1, At, B1); PG8_BAR; PG8_SCHED;
	s_waitcnt lgkmcnt(0)
	v_mfma_f32_16x16x32_bf16 v[60:63], v[128:131], v[176:179], v[60:63]
	v_mfma_f32_16x16x32_bf16 v[56:59], v[136:139], v[176:179], v[56:59]
	v_mfma_f32_16x16x32_bf16 v[44:47], v[128:131], v[184:187], v[44:47]
	v_mfma_f32_16x16x32_bf16 v[40:43], v[136:139], v[184:187], v[40:43]
	v_mfma_f32_16x16x32_bf16 v[28:31], v[128:131], v[202:205], v[28:31]
	v_mfma_f32_16x16x32_bf16 v[24:27], v[136:139], v[202:205], v[24:27]
	v_mfma_f32_16x16x32_bf16 v[12:15], v[128:131], v[210:213], v[12:15]
	v_mfma_f32_16x16x32_bf16 v[8:11], v[136:139], v[210:213], v[8:11]
	v_mfma_f32_16x16x32_bf16 v[60:63], v[132:135], v[180:183], v[60:63]
	v_mfma_f32_16x16x32_bf16 v[56:59], v[140:143], v[180:183], v[56:59]
	v_mfma_f32_16x16x32_bf16 v[44:47], v[132:135], v[188:191], v[44:47]
	v_mfma_f32_16x16x32_bf16 v[40:43], v[140:143], v[188:191], v[40:43]
	v_mfma_f32_16x16x32_bf16 v[28:31], v[132:135], v[206:209], v[28:31]
	v_mfma_f32_16x16x32_bf16 v[24:27], v[140:143], v[206:209], v[24:27]
	v_mfma_f32_16x16x32_bf16 v[12:15], v[132:135], v[214:217], v[12:15]
	v_mfma_f32_16x16x32_bf16 v[8:11], v[140:143], v[214:217], v[8:11]
	v_mfma_f32_16x16x32_bf16 v[52:55], v[160:163], v[176:179], v[52:55]
	v_mfma_f32_16x16x32_bf16 v[48:51], v[168:171], v[176:179], v[48:51]
	v_mfma_f32_16x16x32_bf16 v[36:39], v[160:163], v[184:187], v[36:39]
	v_mfma_f32_16x16x32_bf16 v[32:35], v[168:171], v[184:187], v[32:35]
	v_mfma_f32_16x16x32_bf16 v[20:23], v[160:163], v[202:205], v[20:23]
	v_mfma_f32_16x16x32_bf16 v[16:19], v[168:171], v[202:205], v[16:19]
	v_mfma_f32_16x16x32_bf16 v[4:7], v[160:163], v[210:213], v[4:7]
	v_mfma_f32_16x16x32_bf16 v[0:3], v[168:171], v[210:213], v[0:3]
	v_mfma_f32_16x16x32_bf16 v[52:55], v[164:167], v[180:183], v[52:55]
	v_mfma_f32_16x16x32_bf16 v[48:51], v[172:175], v[180:183], v[48:51]
	v_mfma_f32_16x16x32_bf16 v[36:39], v[164:167], v[188:191], v[36:39]
	v_mfma_f32_16x16x32_bf16 v[32:35], v[172:175], v[188:191], v[32:35]
	v_mfma_f32_16x16x32_bf16 v[20:23], v[164:167], v[206:209], v[20:23]
	v_mfma_f32_16x16x32_bf16 v[16:19], v[172:175], v[206:209], v[16:19]
	v_mfma_f32_16x16x32_bf16 v[4:7], v[164:167], v[214:217], v[4:7]
	v_mfma_f32_16x16x32_bf16 v[0:3], v[172:175], v[214:217], v[0:3]
	s_barrier
	s_add_i32 s24, 0, 0x18000
	s_add_i32 s26, 0, 0x1c000
	v_add_u32_e32 v140, s24, v158
	v_add_u32_e32 v172, s26, v158
	ds_read_b128 v[128:131], v140
	ds_read_b128 v[132:135], v140 offset:1024
	ds_read_b128 v[136:139], v140 offset:2048
	ds_read_b128 v[140:143], v140 offset:3072
	ds_read_b128 v[160:163], v172
	ds_read_b128 v[164:167], v172 offset:1024
	ds_read_b128 v[168:171], v172 offset:2048
	ds_read_b128 v[172:175], v172 offset:3072
	s_add_u32 s48, s48, 0x80000
	s_addc_u32 s49, s49, 0
	s_mov_b32 m0, s52
	v_lshl_add_u64 v[234:235], s[48:49], 0, v[144:145]
	ds_read_b128 v[176:179], v159 offset:32768
	ds_read_b128 v[180:183], v159 offset:33792
	ds_read_b128 v[184:187], v159 offset:34816
	ds_read_b128 v[188:191], v159 offset:35840
	ds_read_b128 v[202:205], v159 offset:36864
	ds_read_b128 v[206:209], v159 offset:37888
	ds_read_b128 v[210:213], v159 offset:38912
	ds_read_b128 v[214:217], v159 offset:39936
	global_load_lds_dwordx4 v[234:235], off
	v_lshl_add_u64 v[234:235], s[48:49], 0, v[146:147]
	s_mov_b32 m0, s53
	s_nop 0
	global_load_lds_dwordx4 v[234:235], off
	s_waitcnt vmcnt(8)
	s_waitcnt lgkmcnt(0)
	s_barrier
	s_waitcnt lgkmcnt(0)
	v_mfma_f32_16x16x32_bf16 v[124:127], v[128:131], v[176:179], v[124:127]
	v_mfma_f32_16x16x32_bf16 v[120:123], v[136:139], v[176:179], v[120:123]
	v_mfma_f32_16x16x32_bf16 v[108:111], v[128:131], v[184:187], v[108:111]
	v_mfma_f32_16x16x32_bf16 v[104:107], v[136:139], v[184:187], v[104:107]
	v_mfma_f32_16x16x32_bf16 v[92:95], v[128:131], v[202:205], v[92:95]
	v_mfma_f32_16x16x32_bf16 v[88:91], v[136:139], v[202:205], v[88:91]
	v_mfma_f32_16x16x32_bf16 v[76:79], v[128:131], v[210:213], v[76:79]
	v_mfma_f32_16x16x32_bf16 v[72:75], v[136:139], v[210:213], v[72:75]
	v_mfma_f32_16x16x32_bf16 v[124:127], v[132:135], v[180:183], v[124:127]
	v_mfma_f32_16x16x32_bf16 v[120:123], v[140:143], v[180:183], v[120:123]
	v_mfma_f32_16x16x32_bf16 v[108:111], v[132:135], v[188:191], v[108:111]
	v_mfma_f32_16x16x32_bf16 v[104:107], v[140:143], v[188:191], v[104:107]
	v_mfma_f32_16x16x32_bf16 v[92:95], v[132:135], v[206:209], v[92:95]
	v_mfma_f32_16x16x32_bf16 v[88:91], v[140:143], v[206:209], v[88:91]
	v_mfma_f32_16x16x32_bf16 v[76:79], v[132:135], v[214:217], v[76:79]
	v_mfma_f32_16x16x32_bf16 v[72:75], v[140:143], v[214:217], v[72:75]
	v_mfma_f32_16x16x32_bf16 v[116:119], v[160:163], v[176:179], v[116:119]
	v_mfma_f32_16x16x32_bf16 v[112:115], v[168:171], v[176:179], v[112:115]
	v_mfma_f32_16x16x32_bf16 v[100:103], v[160:163], v[184:187], v[100:103]
	v_mfma_f32_16x16x32_bf16 v[96:99], v[168:171], v[184:187], v[96:99]
	v_mfma_f32_16x16x32_bf16 v[84:87], v[160:163], v[202:205], v[84:87]
	v_mfma_f32_16x16x32_bf16 v[80:83], v[168:171], v[202:205], v[80:83]
	v_mfma_f32_16x16x32_bf16 v[68:71], v[160:163], v[210:213], v[68:71]
	v_mfma_f32_16x16x32_bf16 v[64:67], v[168:171], v[210:213], v[64:67]
	v_mfma_f32_16x16x32_bf16 v[116:119], v[164:167], v[180:183], v[116:119]
	v_mfma_f32_16x16x32_bf16 v[112:115], v[172:175], v[180:183], v[112:115]
	v_mfma_f32_16x16x32_bf16 v[100:103], v[164:167], v[188:191], v[100:103]
	v_mfma_f32_16x16x32_bf16 v[96:99], v[172:175], v[188:191], v[96:99]
	v_mfma_f32_16x16x32_bf16 v[84:87], v[164:167], v[206:209], v[84:87]
	v_mfma_f32_16x16x32_bf16 v[80:83], v[172:175], v[206:209], v[80:83]
	v_mfma_f32_16x16x32_bf16 v[68:71], v[164:167], v[214:217], v[68:71]
	v_mfma_f32_16x16x32_bf16 v[64:67], v[172:175], v[214:217], v[64:67]
	s_barrier
; #define PG8_STAGE(bufoff, gbase, voff) do { _Pragma("unroll") for (int _i = 0; _i < 2; ++_i) \
;         __builtin_amdgcn_global_load_lds((const unsigned*)((const char*)(gbase) + (voff)[_i]), (LAS unsigned*)(lds + (bufoff) + ldsw + _i * 8192), 16, 0, 0); } while (0)
; #define PG8_LDA(dst, b, h) do { _Pragma("unroll") for (int m = 0; m < 4; ++m) _Pragma("unroll") for (int k = 0; k < 2; ++k) dst[m][k] = *(const LAS bf16x8*)(lds + PG8_SA(b, h) + aoff + m * 2048 + k * 1024); } while (0)
; #define PG8_MMA(ai, bj, At, Bt) do { __builtin_amdgcn_s_setprio(1); _Pragma("unroll") for (int m = 0; m < 4; ++m) _Pragma("unroll") for (int n = 0; n < 2; ++n) _Pragma("unroll") for (int k = 0; k < 2; ++k) \
;         acc[ai][bj][m][n] = __builtin_amdgcn_mfma_f32_16x16x32_bf16(Bt[n][k], At[m][k], acc[ai][bj][m][n], 0, 0, 0); __builtin_amdgcn_s_setprio(0); } while (0)
; #define PG8_WAIT_V(n) asm volatile("s_waitcnt vmcnt(" #n ")" ::: "memory")
; #define PG8_WAIT_L(n) asm volatile("s_waitcnt lgkmcnt(" #n ")" ::: "memory")
; #define PG8_BAR __builtin_amdgcn_s_barrier()
; #define PG8_SCHED __builtin_amdgcn_sched_barrier(0)
; template <class Epi, class Sched>
; __device__ __forceinline__ void gemm_phase(LAS unsigned char* lds, const Gemm g, const Sched& S, const Epi& E, const int tid) {
;     ...
;             PG8_LDA(At, 1, 1); PG8_STAGE(PG8_SB(1, 0), b3, voffB); PG8_STAGE(PG8_SB(1, 1), b3 + hstepB, voffB); PG8_STAGE(PG8_SA(1, 0), a3, voffA);
;             PG8_WAIT_V(8); PG8_WAIT_L(0); PG8_BAR; PG8_MMA(1, 0, At, B0); PG8_MMA(1, 1, At, B1); PG8_BAR; PG8_SCHED;
;         }
	s_add_i32 s24, s24, s25
	v_lshl_add_u64 v[154:155], v[154:155], 0, s[34:35]
	s_mov_b32 m0, s24
	ds_read_b128 v[176:179], v159 offset:49152
	ds_read_b128 v[180:183], v159 offset:50176
	ds_read_b128 v[184:187], v159 offset:51200
	ds_read_b128 v[188:191], v159 offset:52224
	ds_read_b128 v[202:205], v159 offset:53248
	ds_read_b128 v[206:209], v159 offset:54272
	ds_read_b128 v[210:213], v159 offset:55296
	ds_read_b128 v[214:217], v159 offset:56320
	global_load_lds_dwordx4 v[154:155], off
	s_add_i32 m0, s24, 0x2000
	s_add_u32 s38, s38, 0x80080
	v_lshl_add_u64 v[154:155], v[218:219], 0, s[34:35]
	s_addc_u32 s39, s39, 0
	s_add_i32 s24, s26, s25
	global_load_lds_dwordx4 v[154:155], off
	v_lshl_add_u64 v[154:155], s[38:39], 0, v[192:193]
	s_mov_b32 m0, s24
	s_nop 0
	global_load_lds_dwordx4 v[154:155], off
	v_lshl_add_u64 v[154:155], s[38:39], 0, v[148:149]
	s_add_i32 m0, s24, 0x2000
	s_nop 0
	global_load_lds_dwordx4 v[154:155], off
	v_lshl_add_u64 v[154:155], v[220:221], 0, s[34:35]
	s_mov_b32 m0, s56
	s_nop 0
	global_load_lds_dwordx4 v[154:155], off
	v_lshl_add_u64 v[154:155], v[222:223], 0, s[34:35]
	s_mov_b32 m0, s57
	s_nop 0
	global_load_lds_dwordx4 v[154:155], off
	s_waitcnt vmcnt(8)
	s_waitcnt lgkmcnt(0)
	s_barrier
	s_waitcnt lgkmcnt(0)
	v_mfma_f32_16x16x32_bf16 v[60:63], v[128:131], v[176:179], v[60:63]
	v_mfma_f32_16x16x32_bf16 v[56:59], v[136:139], v[176:179], v[56:59]
	v_mfma_f32_16x16x32_bf16 v[44:47], v[128:131], v[184:187], v[44:47]
	v_mfma_f32_16x16x32_bf16 v[40:43], v[136:139], v[184:187], v[40:43]
	v_mfma_f32_16x16x32_bf16 v[28:31], v[128:131], v[202:205], v[28:31]
	v_mfma_f32_16x16x32_bf16 v[24:27], v[136:139], v[202:205], v[24:27]
	v_mfma_f32_16x16x32_bf16 v[12:15], v[128:131], v[210:213], v[12:15]
	v_mfma_f32_16x16x32_bf16 v[8:11], v[136:139], v[210:213], v[8:11]
	v_mfma_f32_16x16x32_bf16 v[60:63], v[132:135], v[180:183], v[60:63]
	v_mfma_f32_16x16x32_bf16 v[56:59], v[140:143], v[180:183], v[56:59]
	v_mfma_f32_16x16x32_bf16 v[44:47], v[132:135], v[188:191], v[44:47]
	v_mfma_f32_16x16x32_bf16 v[40:43], v[140:143], v[188:191], v[40:43]
	v_mfma_f32_16x16x32_bf16 v[28:31], v[132:135], v[206:209], v[28:31]
	v_mfma_f32_16x16x32_bf16 v[24:27], v[140:143], v[206:209], v[24:27]
	v_mfma_f32_16x16x32_bf16 v[12:15], v[132:135], v[214:217], v[12:15]
	v_mfma_f32_16x16x32_bf16 v[8:11], v[140:143], v[214:217], v[8:11]
	v_mfma_f32_16x16x32_bf16 v[52:55], v[160:163], v[176:179], v[52:55]
	v_mfma_f32_16x16x32_bf16 v[48:51], v[168:171], v[176:179], v[48:51]
	v_mfma_f32_16x16x32_bf16 v[36:39], v[160:163], v[184:187], v[36:39]
	v_mfma_f32_16x16x32_bf16 v[32:35], v[168:171], v[184:187], v[32:35]
	v_mfma_f32_16x16x32_bf16 v[20:23], v[160:163], v[202:205], v[20:23]
	v_mfma_f32_16x16x32_bf16 v[16:19], v[168:171], v[202:205], v[16:19]
	v_mfma_f32_16x16x32_bf16 v[4:7], v[160:163], v[210:213], v[4:7]
	v_mfma_f32_16x16x32_bf16 v[0:3], v[168:171], v[210:213], v[0:3]
	v_mfma_f32_16x16x32_bf16 v[52:55], v[164:167], v[180:183], v[52:55]
	v_mfma_f32_16x16x32_bf16 v[48:51], v[172:175], v[180:183], v[48:51]
	v_mfma_f32_16x16x32_bf16 v[36:39], v[164:167], v[188:191], v[36:39]
	v_mfma_f32_16x16x32_bf16 v[32:35], v[172:175], v[188:191], v[32:35]
	v_mfma_f32_16x16x32_bf16 v[20:23], v[164:167], v[206:209], v[20:23]
	v_mfma_f32_16x16x32_bf16 v[16:19], v[172:175], v[206:209], v[16:19]
	v_mfma_f32_16x16x32_bf16 v[4:7], v[164:167], v[214:217], v[4:7]
	v_mfma_f32_16x16x32_bf16 v[0:3], v[172:175], v[214:217], v[0:3]
	s_barrier
	s_add_i32 s22, s22, 2
	s_add_u32 s2, s2, 0x100
	s_addc_u32 s3, s3, 0
	s_add_u32 s20, s20, 0x100
	s_addc_u32 s21, s21, 0
	s_cmp_gt_u32 s22, 29
	s_cbranch_scc0 .LBB0_347
	s_and_b64 vcc, exec, s[8:9]
	s_cbranch_vccz .LBB0_350
	s_barrier
